# fb_sample loop rewritten: 8 sixteen-row groups per iteration with all loads in flight, scalar addressing, constant vmcnt(7)
# baseline (speedup 1.0000x reference)
.LBB0_51:
	v_and_b32_e32 v5, 63, v141
	v_readfirstlane_b32 s14, v8
	v_and_b32_e32 v6, 15, v5
	v_lshrrev_b32_e32 v7, 4, v5
	v_lshlrev_b32_e32 v9, 6, v6
	v_lshl_add_u32 v9, v7, 4, v9
	v_lshlrev_b32_e32 v10, 18, v6
	v_lshl_add_u32 v10, v7, 3, v10
	v_readlane_b32 s0, v252, 29
	v_readlane_b32 s1, v252, 30
	s_add_u32 s40, s6, 0x2000000
	s_addc_u32 s41, s7, 0
.Lfbs_loop:
	s_mov_b32 s15, s14
	s_lshl_b32 s12, s14, 10
	s_add_u32 s4, s0, s12
	s_addc_u32 s5, s1, 0
	global_load_dwordx4 v[16:19], v9, s[4:5]
	s_add_i32 s15, s15, s24
	s_cmp_lt_u32 s15, 0x20000
	s_cselect_b32 s43, s15, s14
	s_lshl_b32 s12, s43, 10
	s_add_u32 s4, s0, s12
	s_addc_u32 s5, s1, 0
	global_load_dwordx4 v[20:23], v9, s[4:5]
	s_add_i32 s15, s15, s24
	s_cmp_lt_u32 s15, 0x20000
	s_cselect_b32 s44, s15, s14
	s_lshl_b32 s12, s44, 10
	s_add_u32 s4, s0, s12
	s_addc_u32 s5, s1, 0
	global_load_dwordx4 v[24:27], v9, s[4:5]
	s_add_i32 s15, s15, s24
	s_cmp_lt_u32 s15, 0x20000
	s_cselect_b32 s45, s15, s14
	s_lshl_b32 s12, s45, 10
	s_add_u32 s4, s0, s12
	s_addc_u32 s5, s1, 0
	global_load_dwordx4 v[28:31], v9, s[4:5]
	s_add_i32 s15, s15, s24
	s_cmp_lt_u32 s15, 0x20000
	s_cselect_b32 s46, s15, s14
	s_lshl_b32 s12, s46, 10
	s_add_u32 s4, s0, s12
	s_addc_u32 s5, s1, 0
	global_load_dwordx4 v[32:35], v9, s[4:5]
	s_add_i32 s15, s15, s24
	s_cmp_lt_u32 s15, 0x20000
	s_cselect_b32 s47, s15, s14
	s_lshl_b32 s12, s47, 10
	s_add_u32 s4, s0, s12
	s_addc_u32 s5, s1, 0
	global_load_dwordx4 v[36:39], v9, s[4:5]
	s_add_i32 s15, s15, s24
	s_cmp_lt_u32 s15, 0x20000
	s_cselect_b32 s48, s15, s14
	s_lshl_b32 s12, s48, 10
	s_add_u32 s4, s0, s12
	s_addc_u32 s5, s1, 0
	global_load_dwordx4 v[40:43], v9, s[4:5]
	s_add_i32 s15, s15, s24
	s_cmp_lt_u32 s15, 0x20000
	s_cselect_b32 s49, s15, s14
	s_lshl_b32 s12, s49, 10
	s_add_u32 s4, s0, s12
	s_addc_u32 s5, s1, 0
	global_load_dwordx4 v[44:47], v9, s[4:5]
	s_add_i32 s15, s15, s24
	s_waitcnt vmcnt(7)
	v_mfma_f32_16x16x32_bf16 v[48:51], v[16:19], v[0:3], 0
	s_lshr_b32 s12, s14, 6
	s_and_b32 s12, s12, 0x7f
	s_lshl_b32 s12, s12, 11
	s_lshr_b32 s13, s14, 13
	s_lshl_b32 s13, s13, 22
	s_add_u32 s12, s12, s13
	s_and_b32 s13, s14, 63
	s_lshl_b32 s13, s13, 5
	s_add_u32 s12, s12, s13
	s_add_u32 s4, s40, s12
	s_addc_u32 s5, s41, 0
	v_cvt_pk_bf16_f32 v56, v48, v49
	v_cvt_pk_bf16_f32 v57, v50, v51
	global_store_dwordx2 v10, v[56:57], s[4:5]
	s_waitcnt vmcnt(7)
	v_mfma_f32_16x16x32_bf16 v[52:55], v[20:23], v[0:3], 0
	s_lshr_b32 s12, s43, 6
	s_and_b32 s12, s12, 0x7f
	s_lshl_b32 s12, s12, 11
	s_lshr_b32 s13, s43, 13
	s_lshl_b32 s13, s13, 22
	s_add_u32 s12, s12, s13
	s_and_b32 s13, s43, 63
	s_lshl_b32 s13, s13, 5
	s_add_u32 s12, s12, s13
	s_add_u32 s4, s40, s12
	s_addc_u32 s5, s41, 0
	v_cvt_pk_bf16_f32 v58, v52, v53
	v_cvt_pk_bf16_f32 v59, v54, v55
	global_store_dwordx2 v10, v[58:59], s[4:5]
	s_waitcnt vmcnt(7)
	v_mfma_f32_16x16x32_bf16 v[48:51], v[24:27], v[0:3], 0
	s_lshr_b32 s12, s44, 6
	s_and_b32 s12, s12, 0x7f
	s_lshl_b32 s12, s12, 11
	s_lshr_b32 s13, s44, 13
	s_lshl_b32 s13, s13, 22
	s_add_u32 s12, s12, s13
	s_and_b32 s13, s44, 63
	s_lshl_b32 s13, s13, 5
	s_add_u32 s12, s12, s13
	s_add_u32 s4, s40, s12
	s_addc_u32 s5, s41, 0
	v_cvt_pk_bf16_f32 v56, v48, v49
	v_cvt_pk_bf16_f32 v57, v50, v51
	global_store_dwordx2 v10, v[56:57], s[4:5]
	s_waitcnt vmcnt(7)
	v_mfma_f32_16x16x32_bf16 v[52:55], v[28:31], v[0:3], 0
	s_lshr_b32 s12, s45, 6
	s_and_b32 s12, s12, 0x7f
	s_lshl_b32 s12, s12, 11
	s_lshr_b32 s13, s45, 13
	s_lshl_b32 s13, s13, 22
	s_add_u32 s12, s12, s13
	s_and_b32 s13, s45, 63
	s_lshl_b32 s13, s13, 5
	s_add_u32 s12, s12, s13
	s_add_u32 s4, s40, s12
	s_addc_u32 s5, s41, 0
	v_cvt_pk_bf16_f32 v58, v52, v53
	v_cvt_pk_bf16_f32 v59, v54, v55
	global_store_dwordx2 v10, v[58:59], s[4:5]
	s_waitcnt vmcnt(7)
	v_mfma_f32_16x16x32_bf16 v[48:51], v[32:35], v[0:3], 0
	s_lshr_b32 s12, s46, 6
	s_and_b32 s12, s12, 0x7f
	s_lshl_b32 s12, s12, 11
	s_lshr_b32 s13, s46, 13
	s_lshl_b32 s13, s13, 22
	s_add_u32 s12, s12, s13
	s_and_b32 s13, s46, 63
	s_lshl_b32 s13, s13, 5
	s_add_u32 s12, s12, s13
	s_add_u32 s4, s40, s12
	s_addc_u32 s5, s41, 0
	v_cvt_pk_bf16_f32 v56, v48, v49
	v_cvt_pk_bf16_f32 v57, v50, v51
	global_store_dwordx2 v10, v[56:57], s[4:5]
	s_waitcnt vmcnt(7)
	v_mfma_f32_16x16x32_bf16 v[52:55], v[36:39], v[0:3], 0
	s_lshr_b32 s12, s47, 6
	s_and_b32 s12, s12, 0x7f
	s_lshl_b32 s12, s12, 11
	s_lshr_b32 s13, s47, 13
	s_lshl_b32 s13, s13, 22
	s_add_u32 s12, s12, s13
	s_and_b32 s13, s47, 63
	s_lshl_b32 s13, s13, 5
	s_add_u32 s12, s12, s13
	s_add_u32 s4, s40, s12
	s_addc_u32 s5, s41, 0
	v_cvt_pk_bf16_f32 v58, v52, v53
	v_cvt_pk_bf16_f32 v59, v54, v55
	global_store_dwordx2 v10, v[58:59], s[4:5]
	s_waitcnt vmcnt(7)
	v_mfma_f32_16x16x32_bf16 v[48:51], v[40:43], v[0:3], 0
	s_lshr_b32 s12, s48, 6
	s_and_b32 s12, s12, 0x7f
	s_lshl_b32 s12, s12, 11
	s_lshr_b32 s13, s48, 13
	s_lshl_b32 s13, s13, 22
	s_add_u32 s12, s12, s13
	s_and_b32 s13, s48, 63
	s_lshl_b32 s13, s13, 5
	s_add_u32 s12, s12, s13
	s_add_u32 s4, s40, s12
	s_addc_u32 s5, s41, 0
	v_cvt_pk_bf16_f32 v56, v48, v49
	v_cvt_pk_bf16_f32 v57, v50, v51
	global_store_dwordx2 v10, v[56:57], s[4:5]
	s_waitcnt vmcnt(7)
	v_mfma_f32_16x16x32_bf16 v[52:55], v[44:47], v[0:3], 0
	s_lshr_b32 s12, s49, 6
	s_and_b32 s12, s12, 0x7f
	s_lshl_b32 s12, s12, 11
	s_lshr_b32 s13, s49, 13
	s_lshl_b32 s13, s13, 22
	s_add_u32 s12, s12, s13
	s_and_b32 s13, s49, 63
	s_lshl_b32 s13, s13, 5
	s_add_u32 s12, s12, s13
	s_add_u32 s4, s40, s12
	s_addc_u32 s5, s41, 0
	v_cvt_pk_bf16_f32 v58, v52, v53
	v_cvt_pk_bf16_f32 v59, v54, v55
	global_store_dwordx2 v10, v[58:59], s[4:5]
	s_mov_b32 s14, s15
	s_cmp_lt_u32 s14, 0x20000
	s_cbranch_scc1 .Lfbs_loop
